# attention PV phase cost-weighted VALU spacing (doc 7.5): row-sum v_add moved from the x-y MFMA gap to after the pair's second MFMA in 31 groups; tail v_pk_add_f32 split into two v_add_f32 (on top of v
# speedup vs baseline: 1.0002x; 1.0002x over previous
; #define ATT_WAIT_BAR() asm volatile("s_waitcnt vmcnt(0) lgkmcnt(0)\n\ts_barrier" ::: "memory")
; #define ATT_SB() __builtin_amdgcn_sched_barrier(0)
; #define A16_VLD(v, g) do { const LAS unsigned char* a_ = vbp[(g) & 3] + vso + ((g) >> 4) * 16384 + (((g) & 15) >> 2) * 1024; v[0] = vtr(a_); v[1] = vtr(a_ + 8192); } while (0)
; #define A16_GAP(i) do { A16_EL(i) = __builtin_amdgcn_exp2f(A16_EL(i)); \
;                 if ((i) > 0) { if ((((i) - 1) >> 2) & 1) s1 += A16_EL((i) - 1); else s0 += A16_EL((i) - 1); } asm volatile("" : "+v"(s0), "+v"(s1)); } while (0)
; __device__ __forceinline__ void attn_core16(f32x4 (&O)[16][2], float (&lq)[2], const bf16_t* Qw, int q_pitch, const bf16_t* Kh, const bf16_t* Vh, int kv_pitch,
;                                             int NT, int nt_act, int kch0, float negb, LAS unsigned char* ring, int wid) {
;     ...
;         ATT_WAIT_BAR();
;         if (t < nt_act) {
;             const bool more = (t + 1 < nt_act);
;             const int vso = (t & 1) * SLOTB;
;             s16x4 vv[3][2];
;     ...
;             A16_VLD(vv[0], 0);
;             ATT_SB();
;             A16_QK(t + 1, 1, t);
;             ATT_SB();
;             A16_VLD(vv[1], 1);
;             float s0 = 0.f, s1 = 0.f;
;     ...
; #pragma unroll
;             for (int g = 0; g < 32; ++g) {
;                 if (g + 2 < 32) A16_VLD(vv[(g + 2) % 3], g + 2);
;                 ATT_SB();
;                 O[g & 15][0] = __builtin_amdgcn_mfma_f32_16x16x32_bf16(A16_VF(vv[g % 3]), __builtin_bit_cast(bf16x8, pw[g >> 4][0]), O[g & 15][0], 0, 0, 0);
;                 O[g & 15][1] = __builtin_amdgcn_mfma_f32_16x16x32_bf16(A16_VF(vv[g % 3]), __builtin_bit_cast(bf16x8, pw[g >> 4][1]), O[g & 15][1], 0, 0, 0);
;                 A16_GAP(g);
;                 ATT_SB();
;             }
.LBB0_685:
	s_waitcnt vmcnt(0) lgkmcnt(0)
	s_barrier
	s_add_i32 s20, s0, 1
	s_cmp_ge_u32 s0, s73
	s_cbranch_scc1 .LBB0_687
	s_and_b32 s80, s72, 0x10000
	v_add_u32_e32 v2, s80, v214
	ds_read_b128 v[188:191], v2
	ds_read_b128 v[192:195], v2 offset:8192
	s_add_i32 s48, s72, 0xffff0000
	s_and_b32 s50, s48, 0x10000
	v_add_u32_e32 v0, s50, v216
	ds_read_b64_tr_b16 v[220:221], v0 offset:32768
	ds_read_b64_tr_b16 v[222:223], v0 offset:40960
	s_add_i32 s0, s0, 2
	s_min_u32 vcc_lo, s0, s21
	s_min_u32 s0, s20, s21
	s_lshl_b64 s[70:71], s[0:1], 18
	s_add_u32 s70, s38, s70
	s_mov_b32 vcc_hi, s1
	ds_read_b128 v[200:203], v2 offset:16384
	s_addc_u32 s71, s39, s71
	s_add_i32 s0, s12, s80
	s_lshl_b64 vcc, vcc, 18
	s_add_u32 s54, s18, vcc_lo
	s_addc_u32 s55, s19, vcc_hi
	s_add_i32 vcc_lo, s13, s50
	s_waitcnt lgkmcnt(4)
	v_mfma_f32_16x16x32_bf16 v[196:199], v[188:191], v[136:139], v[168:171]
	s_mov_b32 m0, vcc_lo
	s_nop 0
	global_load_lds_dwordx4 v212, s[54:55]
	v_mfma_f32_16x16x32_bf16 v[188:191], v[188:191], v[152:155], v[168:171]
	ds_read_b128 v[204:207], v2 offset:24576
	s_add_u32 s48, s54, 0x80
	s_waitcnt lgkmcnt(2)
	v_mfma_f32_16x16x32_bf16 v[224:227], v[192:195], v[136:139], v[168:171]
	s_addc_u32 s49, s55, 0
	s_add_i32 vcc_hi, vcc_lo, 0x400
	s_mov_b32 m0, vcc_hi
	s_nop 0
	global_load_lds_dwordx4 v212, s[48:49]
	v_mfma_f32_16x16x32_bf16 v[192:195], v[192:195], v[152:155], v[168:171]
	v_add_u32_e32 v3, s80, v215
	ds_read_b128 v[230:233], v3
	s_add_u32 s48, s54, 0x100
	s_waitcnt lgkmcnt(2)
	v_mfma_f32_16x16x32_bf16 v[234:237], v[200:203], v[136:139], v[168:171]
	s_addc_u32 s49, s55, 0
	s_add_i32 s9, vcc_lo, 0x800
	s_mov_b32 m0, s9
	s_nop 0
	global_load_lds_dwordx4 v212, s[48:49]
	v_mfma_f32_16x16x32_bf16 v[200:203], v[200:203], v[152:155], v[168:171]
	ds_read_b128 v[238:241], v3 offset:8192
	s_add_u32 s48, s54, 0x180
	s_waitcnt lgkmcnt(2)
	v_mfma_f32_16x16x32_bf16 v[242:245], v[204:207], v[136:139], v[168:171]
	s_addc_u32 s49, s55, 0
	s_add_i32 s9, vcc_lo, 0xc00
	s_mov_b32 m0, s9
	s_nop 0
	global_load_lds_dwordx4 v212, s[48:49]
	v_mfma_f32_16x16x32_bf16 v[204:207], v[204:207], v[152:155], v[168:171]
	ds_read_b128 v[246:249], v3 offset:16384
	s_waitcnt lgkmcnt(2)
	v_mfma_f32_16x16x32_bf16 v[196:199], v[230:233], v[140:143], v[196:199]
	s_mov_b32 m0, s0
	s_nop 0
	global_load_lds_dwordx4 v213, s[70:71]
	v_mfma_f32_16x16x32_bf16 v[188:191], v[230:233], v[156:159], v[188:191]
	ds_read_b128 v[230:233], v3 offset:24576
	s_add_u32 s48, s70, 0x80
	s_waitcnt lgkmcnt(2)
	v_mfma_f32_16x16x32_bf16 v[192:195], v[238:241], v[156:159], v[192:195]
	s_addc_u32 s49, s71, 0
	s_add_i32 s9, s0, 0x400
	s_mov_b32 m0, s9
	s_nop 0
	global_load_lds_dwordx4 v213, s[48:49]
	v_mfma_f32_16x16x32_bf16 v[224:227], v[238:241], v[140:143], v[224:227]
	ds_read_b128 v[238:241], v2 offset:1024
	s_add_u32 s48, s70, 0x100
	s_waitcnt lgkmcnt(2)
	v_mfma_f32_16x16x32_bf16 v[234:237], v[246:249], v[140:143], v[234:237]
	s_addc_u32 s49, s71, 0
	s_add_i32 s9, s0, 0x800
	s_mov_b32 m0, s9
	s_nop 0
	global_load_lds_dwordx4 v213, s[48:49]
	v_mfma_f32_16x16x32_bf16 v[200:203], v[246:249], v[156:159], v[200:203]
	ds_read_b128 v[246:249], v2 offset:9216
	s_add_u32 s48, s70, 0x180
	s_waitcnt lgkmcnt(2)
	v_mfma_f32_16x16x32_bf16 v[204:207], v[230:233], v[156:159], v[204:207]
	s_addc_u32 s49, s71, 0
	s_addk_i32 s0, 0xc00
	s_mov_b32 m0, s0
	s_nop 0
	global_load_lds_dwordx4 v213, s[48:49]
	v_mfma_f32_16x16x32_bf16 v[242:245], v[230:233], v[140:143], v[242:245]
	ds_read_b128 v[230:233], v2 offset:17408
	s_waitcnt lgkmcnt(2)
	v_mfma_f32_16x16x32_bf16 v[196:199], v[238:241], v[144:147], v[196:199]
	v_mfma_f32_16x16x32_bf16 v[188:191], v[238:241], v[160:163], v[188:191]
	ds_read_b128 v[238:241], v2 offset:25600
	s_waitcnt lgkmcnt(2)
	v_mfma_f32_16x16x32_bf16 v[192:195], v[246:249], v[160:163], v[192:195]
	v_mfma_f32_16x16x32_bf16 v[224:227], v[246:249], v[144:147], v[224:227]
	ds_read_b128 v[246:249], v3 offset:1024
	s_waitcnt lgkmcnt(2)
	v_mfma_f32_16x16x32_bf16 v[234:237], v[230:233], v[144:147], v[234:237]
	v_mfma_f32_16x16x32_bf16 v[230:233], v[230:233], v[160:163], v[200:203]
	s_nop 2
	ds_read_b128 v[200:203], v3 offset:9216
	s_waitcnt lgkmcnt(2)
	v_mfma_f32_16x16x32_bf16 v[242:245], v[238:241], v[144:147], v[242:245]
	v_mfma_f32_16x16x32_bf16 v[238:241], v[238:241], v[160:163], v[204:207]
	s_waitcnt lgkmcnt(1)
	v_mfma_f32_16x16x32_bf16 v[250:253], v[246:249], v[148:151], v[196:199]
	s_nop 2
	ds_read_b128 v[196:199], v3 offset:17408
	v_mfma_f32_16x16x32_bf16 v[246:249], v[246:249], v[164:167], v[188:191]
	s_nop 2
	ds_read_b128 v[188:191], v3 offset:25600
	s_waitcnt lgkmcnt(2)
	v_mfma_f32_16x16x32_bf16 v[224:227], v[200:203], v[148:151], v[224:227]
	v_mfma_f32_16x16x32_bf16 v[204:207], v[200:203], v[164:167], v[192:195]
	s_waitcnt lgkmcnt(1)
	v_mfma_f32_16x16x32_bf16 v[200:203], v[196:199], v[148:151], v[234:237]
	v_mfma_f32_16x16x32_bf16 v[196:199], v[196:199], v[164:167], v[230:233]
	s_waitcnt lgkmcnt(0)
	v_mfma_f32_16x16x32_bf16 v[192:195], v[188:191], v[148:151], v[242:245]
	v_mfma_f32_16x16x32_bf16 v[188:191], v[188:191], v[164:167], v[238:241]
	v_add_u32_e32 v229, s50, v217
	s_nop 1
	v_add_u32_e32 v238, s50, v218
	ds_read_b64_tr_b16 v[230:231], v229 offset:32768
	ds_read_b64_tr_b16 v[232:233], v229 offset:40960
	ds_read_b64_tr_b16 v[234:235], v238 offset:32768
	ds_read_b64_tr_b16 v[236:237], v238 offset:40960
	v_mfma_f32_16x16x32_bf16 v[68:71], v[220:223], v[184:187], v[68:71]
	v_mov_b32_e32 v239, 0
	v_mov_b32_e32 v240, 0
	v_exp_f32_e32 v2, v250
	v_mfma_f32_16x16x32_bf16 v[132:135], v[220:223], v[180:183], v[132:135]
	v_add_u32_e32 v241, s50, v219
	ds_read_b64_tr_b16 v[220:221], v241 offset:32768
	ds_read_b64_tr_b16 v[222:223], v241 offset:40960
	s_waitcnt lgkmcnt(4)
; #define ATT_SB() __builtin_amdgcn_sched_barrier(0)
; #define A16_VLD(v, g) do { const LAS unsigned char* a_ = vbp[(g) & 3] + vso + ((g) >> 4) * 16384 + (((g) & 15) >> 2) * 1024; v[0] = vtr(a_); v[1] = vtr(a_ + 8192); } while (0)
; #define A16_GAP(i) do { A16_EL(i) = __builtin_amdgcn_exp2f(A16_EL(i)); \
;                 if ((i) > 0) { if ((((i) - 1) >> 2) & 1) s1 += A16_EL((i) - 1); else s0 += A16_EL((i) - 1); } asm volatile("" : "+v"(s0), "+v"(s1)); } while (0)
; __device__ __forceinline__ void attn_core16(f32x4 (&O)[16][2], float (&lq)[2], const bf16_t* Qw, int q_pitch, const bf16_t* Kh, const bf16_t* Vh, int kv_pitch,
;                                             int NT, int nt_act, int kch0, float negb, LAS unsigned char* ring, int wid) {
;     ...
; #pragma unroll
;             for (int g = 0; g < 32; ++g) {
;                 if (g + 2 < 32) A16_VLD(vv[(g + 2) % 3], g + 2);
;                 ATT_SB();
;                 O[g & 15][0] = __builtin_amdgcn_mfma_f32_16x16x32_bf16(A16_VF(vv[g % 3]), __builtin_bit_cast(bf16x8, pw[g >> 4][0]), O[g & 15][0], 0, 0, 0);
;                 O[g & 15][1] = __builtin_amdgcn_mfma_f32_16x16x32_bf16(A16_VF(vv[g % 3]), __builtin_bit_cast(bf16x8, pw[g >> 4][1]), O[g & 15][1], 0, 0, 0);
;                 A16_GAP(g);
;                 ATT_SB();
;             }
	v_mfma_f32_16x16x32_bf16 v[128:131], v[230:233], v[180:183], v[128:131]
	v_exp_f32_e32 v3, v251
	v_mfma_f32_16x16x32_bf16 v[64:67], v[230:233], v[184:187], v[64:67]
	v_add_f32_e32 v239, v2, v239
	ds_read_b64_tr_b16 v[230:231], v0 offset:33792
	ds_read_b64_tr_b16 v[232:233], v0 offset:41984
	s_waitcnt lgkmcnt(4)
	v_mfma_f32_16x16x32_bf16 v[60:63], v[234:237], v[184:187], v[60:63]
	v_exp_f32_e32 v242, v252
	v_mfma_f32_16x16x32_bf16 v[124:127], v[234:237], v[180:183], v[124:127]
	v_add_f32_e32 v239, v3, v239
	ds_read_b64_tr_b16 v[234:235], v229 offset:33792
	ds_read_b64_tr_b16 v[236:237], v229 offset:41984
	s_waitcnt lgkmcnt(4)
	v_mfma_f32_16x16x32_bf16 v[120:123], v[220:223], v[180:183], v[120:123]
	v_exp_f32_e32 v243, v253
	v_mfma_f32_16x16x32_bf16 v[56:59], v[220:223], v[184:187], v[56:59]
	v_add_f32_e32 v239, v242, v239
	ds_read_b64_tr_b16 v[220:221], v238 offset:33792
	ds_read_b64_tr_b16 v[222:223], v238 offset:41984
	s_waitcnt lgkmcnt(4)
	v_mfma_f32_16x16x32_bf16 v[52:55], v[230:233], v[184:187], v[52:55]
	v_exp_f32_e32 v244, v246
	v_mfma_f32_16x16x32_bf16 v[116:119], v[230:233], v[180:183], v[116:119]
	v_add_f32_e32 v239, v243, v239
	ds_read_b64_tr_b16 v[230:231], v241 offset:33792
	ds_read_b64_tr_b16 v[232:233], v241 offset:41984
	s_waitcnt lgkmcnt(4)
	v_mfma_f32_16x16x32_bf16 v[112:115], v[234:237], v[180:183], v[112:115]
	v_exp_f32_e32 v245, v247
	v_mfma_f32_16x16x32_bf16 v[48:51], v[234:237], v[184:187], v[48:51]
	v_add_f32_e32 v240, v244, v240
	ds_read_b64_tr_b16 v[234:235], v0 offset:34816
	ds_read_b64_tr_b16 v[236:237], v0 offset:43008
	s_waitcnt lgkmcnt(4)
	v_mfma_f32_16x16x32_bf16 v[44:47], v[220:223], v[184:187], v[44:47]
	v_exp_f32_e32 v246, v248
	v_mfma_f32_16x16x32_bf16 v[108:111], v[220:223], v[180:183], v[108:111]
	v_add_f32_e32 v240, v245, v240
	ds_read_b64_tr_b16 v[220:221], v229 offset:34816
	ds_read_b64_tr_b16 v[222:223], v229 offset:43008
	s_waitcnt lgkmcnt(4)
	v_mfma_f32_16x16x32_bf16 v[104:107], v[230:233], v[180:183], v[104:107]
	v_exp_f32_e32 v247, v249
	v_mfma_f32_16x16x32_bf16 v[40:43], v[230:233], v[184:187], v[40:43]
	v_add_f32_e32 v240, v246, v240
	ds_read_b64_tr_b16 v[230:231], v238 offset:34816
	ds_read_b64_tr_b16 v[232:233], v238 offset:43008
	s_waitcnt lgkmcnt(4)
	v_mfma_f32_16x16x32_bf16 v[36:39], v[234:237], v[184:187], v[36:39]
	v_exp_f32_e32 v248, v224
	v_mfma_f32_16x16x32_bf16 v[100:103], v[234:237], v[180:183], v[100:103]
	v_add_f32_e32 v240, v247, v240
	ds_read_b64_tr_b16 v[234:235], v241 offset:34816
	ds_read_b64_tr_b16 v[236:237], v241 offset:43008
	s_waitcnt lgkmcnt(4)
	v_mfma_f32_16x16x32_bf16 v[96:99], v[220:223], v[180:183], v[96:99]
	v_exp_f32_e32 v249, v225
	v_mfma_f32_16x16x32_bf16 v[32:35], v[220:223], v[184:187], v[32:35]
	v_add_f32_e32 v224, v248, v239
	ds_read_b64_tr_b16 v[220:221], v0 offset:35840
	ds_read_b64_tr_b16 v[222:223], v0 offset:44032
	s_waitcnt lgkmcnt(4)
	v_mfma_f32_16x16x32_bf16 v[28:31], v[230:233], v[184:187], v[28:31]
	v_exp_f32_e32 v239, v226
	v_mfma_f32_16x16x32_bf16 v[92:95], v[230:233], v[180:183], v[92:95]
	v_add_f32_e32 v224, v249, v224
	ds_read_b64_tr_b16 v[230:231], v229 offset:35840
	ds_read_b64_tr_b16 v[232:233], v229 offset:44032
	s_waitcnt lgkmcnt(4)
	v_mfma_f32_16x16x32_bf16 v[88:91], v[234:237], v[180:183], v[88:91]
	v_exp_f32_e32 v250, v227
	v_mfma_f32_16x16x32_bf16 v[24:27], v[234:237], v[184:187], v[24:27]
	v_add_f32_e32 v251, v239, v224
	ds_read_b64_tr_b16 v[224:225], v238 offset:35840
	ds_read_b64_tr_b16 v[226:227], v238 offset:44032
	s_waitcnt lgkmcnt(4)
	v_mfma_f32_16x16x32_bf16 v[20:23], v[220:223], v[184:187], v[20:23]
	v_exp_f32_e32 v234, v204
	v_mfma_f32_16x16x32_bf16 v[84:87], v[220:223], v[180:183], v[84:87]
	v_add_f32_e32 v204, v250, v251
	ds_read_b64_tr_b16 v[220:221], v241 offset:35840
	ds_read_b64_tr_b16 v[222:223], v241 offset:44032
	s_waitcnt lgkmcnt(4)
	v_mfma_f32_16x16x32_bf16 v[80:83], v[230:233], v[180:183], v[80:83]
	v_exp_f32_e32 v235, v205
	v_mfma_f32_16x16x32_bf16 v[16:19], v[230:233], v[184:187], v[16:19]
	v_add_f32_e32 v205, v234, v240
	ds_read_b64_tr_b16 v[230:231], v0 offset:49152
	ds_read_b64_tr_b16 v[232:233], v0 offset:57344
	s_waitcnt lgkmcnt(4)
	v_mfma_f32_16x16x32_bf16 v[12:15], v[224:227], v[184:187], v[12:15]
	v_exp_f32_e32 v236, v206
	v_mfma_f32_16x16x32_bf16 v[76:79], v[224:227], v[180:183], v[76:79]
	v_add_f32_e32 v205, v235, v205
	ds_read_b64_tr_b16 v[224:225], v229 offset:49152
	ds_read_b64_tr_b16 v[226:227], v229 offset:57344
	s_waitcnt lgkmcnt(4)
	v_mfma_f32_16x16x32_bf16 v[8:11], v[220:223], v[184:187], v[8:11]
	v_exp_f32_e32 v237, v207
	v_mfma_f32_16x16x32_bf16 v[72:75], v[220:223], v[180:183], v[72:75]
	v_add_f32_e32 v184, v236, v205
	ds_read_b64_tr_b16 v[180:181], v238 offset:49152
	ds_read_b64_tr_b16 v[182:183], v238 offset:57344
	s_waitcnt lgkmcnt(4)
	v_mfma_f32_16x16x32_bf16 v[68:71], v[230:233], v[176:179], v[68:71]
	v_exp_f32_e32 v220, v200
	v_mfma_f32_16x16x32_bf16 v[132:135], v[230:233], v[172:175], v[132:135]
	v_add_f32_e32 v221, v237, v184
	ds_read_b64_tr_b16 v[184:185], v241 offset:49152
	ds_read_b64_tr_b16 v[186:187], v241 offset:57344
	s_waitcnt lgkmcnt(4)
; #define ATT_SB() __builtin_amdgcn_sched_barrier(0)
; #define A16_PACK() do { _Pragma("unroll") for (int p_ = 0; p_ < 2; ++p_) _Pragma("unroll") for (int h_ = 0; h_ < 2; ++h_) \
;         pw[p_][h_] = (u32x4){pk2(S[2 * p_][h_][0], S[2 * p_][h_][1]), pk2(S[2 * p_][h_][2], S[2 * p_][h_][3]), pk2(S[2 * p_ + 1][h_][0], S[2 * p_ + 1][h_][1]), pk2(S[2 * p_ + 1][h_][2], S[2 * p_ + 1][h_][3])}; } while (0)
; #define A16_VLD(v, g) do { const LAS unsigned char* a_ = vbp[(g) & 3] + vso + ((g) >> 4) * 16384 + (((g) & 15) >> 2) * 1024; v[0] = vtr(a_); v[1] = vtr(a_ + 8192); } while (0)
; #define A16_GAP(i) do { A16_EL(i) = __builtin_amdgcn_exp2f(A16_EL(i)); \
;                 if ((i) > 0) { if ((((i) - 1) >> 2) & 1) s1 += A16_EL((i) - 1); else s0 += A16_EL((i) - 1); } asm volatile("" : "+v"(s0), "+v"(s1)); } while (0)
; __device__ __forceinline__ void attn_core16(f32x4 (&O)[16][2], float (&lq)[2], const bf16_t* Qw, int q_pitch, const bf16_t* Kh, const bf16_t* Vh, int kv_pitch,
;                                             int NT, int nt_act, int kch0, float negb, LAS unsigned char* ring, int wid) {
;     ...
; #pragma unroll
;             for (int g = 0; g < 32; ++g) {
;                 if (g + 2 < 32) A16_VLD(vv[(g + 2) % 3], g + 2);
;                 ATT_SB();
;                 O[g & 15][0] = __builtin_amdgcn_mfma_f32_16x16x32_bf16(A16_VF(vv[g % 3]), __builtin_bit_cast(bf16x8, pw[g >> 4][0]), O[g & 15][0], 0, 0, 0);
;                 O[g & 15][1] = __builtin_amdgcn_mfma_f32_16x16x32_bf16(A16_VF(vv[g % 3]), __builtin_bit_cast(bf16x8, pw[g >> 4][1]), O[g & 15][1], 0, 0, 0);
;                 A16_GAP(g);
;                 ATT_SB();
;             }
;     ...
;             l0 += more ? s0 : 0.f; l1 += more ? (s1 + A16_EL(31)) : 0.f;
;             A16_PACK();
	v_mfma_f32_16x16x32_bf16 v[128:131], v[224:227], v[172:175], v[128:131]
	v_exp_f32_e32 v222, v201
	v_mfma_f32_16x16x32_bf16 v[64:67], v[224:227], v[176:179], v[64:67]
	v_add_f32_e32 v200, v220, v204
	ds_read_b64_tr_b16 v[204:205], v0 offset:50176
	ds_read_b64_tr_b16 v[206:207], v0 offset:58368
	s_waitcnt lgkmcnt(4)
	v_mfma_f32_16x16x32_bf16 v[60:63], v[180:183], v[176:179], v[60:63]
	v_exp_f32_e32 v223, v202
	v_mfma_f32_16x16x32_bf16 v[124:127], v[180:183], v[172:175], v[124:127]
	v_add_f32_e32 v200, v222, v200
	ds_read_b64_tr_b16 v[180:181], v229 offset:50176
	ds_read_b64_tr_b16 v[182:183], v229 offset:58368
	s_waitcnt lgkmcnt(4)
	v_mfma_f32_16x16x32_bf16 v[120:123], v[184:187], v[172:175], v[120:123]
	v_exp_f32_e32 v224, v203
	v_mfma_f32_16x16x32_bf16 v[56:59], v[184:187], v[176:179], v[56:59]
	v_add_f32_e32 v200, v223, v200
	ds_read_b64_tr_b16 v[184:185], v238 offset:50176
	ds_read_b64_tr_b16 v[186:187], v238 offset:58368
	s_waitcnt lgkmcnt(4)
	v_mfma_f32_16x16x32_bf16 v[52:55], v[204:207], v[176:179], v[52:55]
	v_exp_f32_e32 v225, v196
	v_mfma_f32_16x16x32_bf16 v[116:119], v[204:207], v[172:175], v[116:119]
	v_add_f32_e32 v226, v224, v200
	ds_read_b64_tr_b16 v[200:201], v241 offset:50176
	ds_read_b64_tr_b16 v[202:203], v241 offset:58368
	s_waitcnt lgkmcnt(4)
	v_mfma_f32_16x16x32_bf16 v[112:115], v[180:183], v[172:175], v[112:115]
	v_exp_f32_e32 v204, v197
	v_mfma_f32_16x16x32_bf16 v[48:51], v[180:183], v[176:179], v[48:51]
	v_add_f32_e32 v196, v225, v221
	ds_read_b64_tr_b16 v[180:181], v0 offset:51200
	ds_read_b64_tr_b16 v[182:183], v0 offset:59392
	s_waitcnt lgkmcnt(4)
	v_mfma_f32_16x16x32_bf16 v[44:47], v[184:187], v[176:179], v[44:47]
	v_exp_f32_e32 v205, v198
	v_mfma_f32_16x16x32_bf16 v[108:111], v[184:187], v[172:175], v[108:111]
	v_add_f32_e32 v196, v204, v196
	ds_read_b64_tr_b16 v[184:185], v229 offset:51200
	ds_read_b64_tr_b16 v[186:187], v229 offset:59392
	s_waitcnt lgkmcnt(4)
	v_mfma_f32_16x16x32_bf16 v[104:107], v[200:203], v[172:175], v[104:107]
	v_exp_f32_e32 v206, v199
	v_mfma_f32_16x16x32_bf16 v[40:43], v[200:203], v[176:179], v[40:43]
	v_add_f32_e32 v207, v205, v196
	ds_read_b64_tr_b16 v[196:197], v238 offset:51200
	ds_read_b64_tr_b16 v[198:199], v238 offset:59392
	s_waitcnt lgkmcnt(4)
	v_mfma_f32_16x16x32_bf16 v[36:39], v[180:183], v[176:179], v[36:39]
	v_exp_f32_e32 v192, v192
	v_mfma_f32_16x16x32_bf16 v[100:103], v[180:183], v[172:175], v[100:103]
	v_add_f32_e32 v200, v206, v207
	ds_read_b64_tr_b16 v[180:181], v241 offset:51200
	ds_read_b64_tr_b16 v[182:183], v241 offset:59392
	s_waitcnt lgkmcnt(4)
	v_mfma_f32_16x16x32_bf16 v[96:99], v[184:187], v[172:175], v[96:99]
	v_exp_f32_e32 v193, v193
	v_mfma_f32_16x16x32_bf16 v[32:35], v[184:187], v[176:179], v[32:35]
	v_add_f32_e32 v201, v192, v226
	ds_read_b64_tr_b16 v[184:185], v0 offset:52224
	ds_read_b64_tr_b16 v[186:187], v0 offset:60416
	s_waitcnt lgkmcnt(4)
	v_mfma_f32_16x16x32_bf16 v[28:31], v[196:199], v[176:179], v[28:31]
	v_exp_f32_e32 v0, v194
	v_mfma_f32_16x16x32_bf16 v[92:95], v[196:199], v[172:175], v[92:95]
	v_add_f32_e32 v194, v193, v201
	ds_read_b64_tr_b16 v[196:197], v229 offset:52224
	ds_read_b64_tr_b16 v[198:199], v229 offset:60416
	s_waitcnt lgkmcnt(4)
	v_mfma_f32_16x16x32_bf16 v[88:91], v[180:183], v[172:175], v[88:91]
	v_exp_f32_e32 v195, v195
	v_mfma_f32_16x16x32_bf16 v[24:27], v[180:183], v[176:179], v[24:27]
	v_add_f32_e32 v194, v0, v194
	ds_read_b64_tr_b16 v[180:181], v238 offset:52224
	ds_read_b64_tr_b16 v[182:183], v238 offset:60416
	s_waitcnt lgkmcnt(4)
	v_mfma_f32_16x16x32_bf16 v[20:23], v[184:187], v[176:179], v[20:23]
	v_exp_f32_e32 v201, v188
	v_mfma_f32_16x16x32_bf16 v[84:87], v[184:187], v[172:175], v[84:87]
	v_add_f32_e32 v188, v195, v194
	ds_read_b64_tr_b16 v[184:185], v241 offset:52224
	ds_read_b64_tr_b16 v[186:187], v241 offset:60416
	s_waitcnt lgkmcnt(4)
	v_mfma_f32_16x16x32_bf16 v[80:83], v[196:199], v[172:175], v[80:83]
	v_exp_f32_e32 v194, v189
	v_mfma_f32_16x16x32_bf16 v[16:19], v[196:199], v[176:179], v[16:19]
	v_add_f32_e32 v189, v201, v200
	s_waitcnt lgkmcnt(2)
	v_mfma_f32_16x16x32_bf16 v[12:15], v[180:183], v[176:179], v[12:15]
	v_exp_f32_e32 v190, v190
	v_mfma_f32_16x16x32_bf16 v[76:79], v[180:183], v[172:175], v[76:79]
	v_add_f32_e32 v189, v194, v189
	s_waitcnt lgkmcnt(0)
	v_mfma_f32_16x16x32_bf16 v[8:11], v[184:187], v[176:179], v[8:11]
	v_exp_f32_e32 v191, v191
	v_mfma_f32_16x16x32_bf16 v[72:75], v[184:187], v[172:175], v[72:75]
	v_add_f32_e32 v176, v190, v189
	s_cmp_lt_u32 s20, s73
	v_add_f32_e32 v172, v191, v176
	s_cselect_b64 vcc, -1, 0
	v_cndmask_b32_e32 v189, 0, v188, vcc
	v_cndmask_b32_e32 v188, 0, v172, vcc
	v_cvt_pk_bf16_f32 v184, v2, v3
	v_cvt_pk_bf16_f32 v185, v242, v243
	v_cvt_pk_bf16_f32 v186, v248, v249
	v_cvt_pk_bf16_f32 v187, v239, v250
	v_cvt_pk_bf16_f32 v180, v244, v245
	v_cvt_pk_bf16_f32 v181, v246, v247
	v_cvt_pk_bf16_f32 v182, v234, v235
	v_cvt_pk_bf16_f32 v183, v236, v237
	v_cvt_pk_bf16_f32 v176, v220, v222
	v_cvt_pk_bf16_f32 v177, v223, v224
	v_cvt_pk_bf16_f32 v178, v192, v193
	v_cvt_pk_bf16_f32 v179, v0, v195
	v_cvt_pk_bf16_f32 v172, v225, v204
	v_cvt_pk_bf16_f32 v173, v205, v206
	v_cvt_pk_bf16_f32 v174, v201, v194
	v_cvt_pk_bf16_f32 v175, v190, v191
	v_add_f32_e32 v208, v208, v188
	v_add_f32_e32 v209, v209, v189
